# plus: sigmoid epilogue scale and +1 as packed f32 ops where register pairs allow (53 fewer VALU per wave and tile)
# speedup vs baseline: 1.0038x; 1.0038x over previous
; __device__ __forceinline__ unsigned pkbf(float lo, float hi) { f32x2p v = {lo, hi}; bf16x2p b = __builtin_convertvector(v, bf16x2p); return __builtin_bit_cast(unsigned, b); }
; __device__ __forceinline__ float sigmoidf_(float x) { return __builtin_amdgcn_rcpf(1.0f + __builtin_amdgcn_exp2f(-x * LOG2E)); }
;     __device__ __forceinline__ void operator()(const f32x4 (&acc)[2][2][4][2], const Unit& u, int wr, int wc, int fr, int fq) const {
;     ...
;                         if constexpr (MODE == EPI_SIG) {
; #pragma unroll
;                             for (int e = 0; e < 4; ++e) { v0[e] = sigmoidf_(v0[e]); v1[e] = sigmoidf_(v1[e]); }
;                         }
;                         if constexpr (MODE == EPI_RELU2) {
; #pragma unroll
;                             for (int e = 0; e < 4; ++e) { float a = fmaxf(v0[e], 0.f), b = fmaxf(v1[e], 0.f); v0[e] = a * a; v1[e] = b * b; }
;                         }
;                         if constexpr (MODE == EPI_GATEMUL) {
;                             const u32x4 gw = *(const u32x4*)(G + off); v0 = v0 * bscale; v1 = v1 * bscale;
;                             v0[0] *= bflo(gw.x); v0[1] *= bfhi(gw.x); v0[2] *= bflo(gw.y); v0[3] *= bfhi(gw.y);
;                             v1[0] *= bflo(gw.z); v1[1] *= bfhi(gw.z); v1[2] *= bflo(gw.w); v1[3] *= bfhi(gw.w);
;                             if (!first) {
;                                 const u32x4 ow = *(const u32x4*)(O + off);
;                                 v0[0] += bflo(ow.x); v0[1] += bfhi(ow.x); v0[2] += bflo(ow.y); v0[3] += bfhi(ow.y);
;                                 v1[0] += bflo(ow.z); v1[1] += bfhi(ow.z); v1[2] += bflo(ow.w); v1[3] += bfhi(ow.w);
;                             }
;                         }
;                         u32x4 w; w.x = pkbf(v0[0], v0[1]); w.y = pkbf(v0[2], v0[3]); w.z = pkbf(v1[0], v1[1]); w.w = pkbf(v1[2], v1[3]);
;                         *(u32x4*)(O + off) = w;
.LBB0_606:
	v_mov_b32_e32 v198, 0xbfb8aa3b
	v_pk_mul_f32 v[126:127], v[126:127], v[198:199] op_sel_hi:[1,0]
	v_pk_mul_f32 v[122:123], v[122:123], v[198:199] op_sel_hi:[1,0]
	v_pk_mul_f32 v[128:129], v[128:129], v[198:199] op_sel_hi:[1,0]
	v_exp_f32_e32 v126, v126
	v_exp_f32_e32 v122, v122
	v_exp_f32_e32 v127, v127
	v_exp_f32_e32 v123, v123
	v_exp_f32_e32 v128, v128
	v_pk_mul_f32 v[124:125], v[124:125], v[198:199] op_sel_hi:[1,0]
	v_exp_f32_e32 v129, v129
	v_exp_f32_e32 v124, v124
	v_exp_f32_e32 v125, v125
	v_pk_add_f32 v[126:127], v[126:127], 1.0 op_sel_hi:[1,0]
	v_pk_add_f32 v[122:123], v[122:123], 1.0 op_sel_hi:[1,0]
	v_pk_add_f32 v[128:129], v[128:129], 1.0 op_sel_hi:[1,0]
	v_rcp_f32_e32 v126, v126
	v_rcp_f32_e32 v122, v122
	v_rcp_f32_e32 v127, v127
	v_rcp_f32_e32 v123, v123
	v_rcp_f32_e32 v128, v128
	v_rcp_f32_e32 v129, v129
	v_pk_add_f32 v[124:125], v[124:125], 1.0 op_sel_hi:[1,0]
	v_rcp_f32_e32 v124, v124
	v_rcp_f32_e32 v125, v125
	v_pk_mul_f32 v[114:115], v[114:115], v[198:199] op_sel_hi:[1,0]
	v_lshl_add_u32 v160, s69, 8, v162
	v_exp_f32_e32 v114, v114
	v_pk_mul_f32 v[118:119], v[118:119], v[198:199] op_sel_hi:[1,0]
	v_lshl_or_b32 v130, s68, 8, v164
	v_ashrrev_i32_e32 v161, 31, v160
	v_exp_f32_e32 v119, v119
	v_ashrrev_i32_e32 v131, 31, v130
	v_cvt_pk_bf16_f32 v126, v126, v127
	v_cvt_pk_bf16_f32 v127, v128, v129
	v_cvt_pk_bf16_f32 v128, v122, v123
	v_lshlrev_b64 v[122:123], 11, v[160:161]
	v_cvt_pk_bf16_f32 v129, v124, v125
	v_lshl_add_u64 v[122:123], s[24:25], 0, v[122:123]
	v_lshlrev_b64 v[124:125], 1, v[130:131]
	v_lshl_add_u64 v[122:123], v[122:123], 0, v[124:125]
	v_add_f32_e32 v114, 1.0, v114
	global_store_dwordx4 v[122:123], v[126:129], off
	v_exp_f32_e32 v115, v115
	v_pk_mul_f32 v[116:117], v[116:117], v[198:199] op_sel_hi:[1,0]
	v_rcp_f32_e32 v126, v114
	v_add_f32_e32 v114, 1.0, v119
	v_mul_f32_e32 v119, 0xbfb8aa3b, v120
	v_exp_f32_e32 v119, v119
	v_add_f32_e32 v115, 1.0, v115
	v_exp_f32_e32 v116, v116
	v_rcp_f32_e32 v120, v115
	v_add_f32_e32 v115, 1.0, v119
	v_mul_f32_e32 v119, 0xbfb8aa3b, v121
	v_exp_f32_e32 v118, v118
	v_exp_f32_e32 v119, v119
	v_exp_f32_e32 v117, v117
	v_add_f32_e32 v116, 1.0, v116
	v_add_f32_e32 v118, 1.0, v118
	v_rcp_f32_e32 v121, v116
	v_add_f32_e32 v116, 1.0, v119
	v_add_f32_e32 v117, 1.0, v117
	v_pk_mul_f32 v[106:107], v[106:107], v[198:199] op_sel_hi:[1,0]
	v_rcp_f32_e32 v118, v118
	v_rcp_f32_e32 v114, v114
	v_rcp_f32_e32 v115, v115
	v_rcp_f32_e32 v116, v116
	v_rcp_f32_e32 v117, v117
	v_exp_f32_e32 v106, v106
	v_pk_mul_f32 v[110:111], v[110:111], v[198:199] op_sel_hi:[1,0]
	v_exp_f32_e32 v111, v111
	v_cvt_pk_bf16_f32 v114, v118, v114
	v_cvt_pk_bf16_f32 v115, v115, v116
	v_cvt_pk_bf16_f32 v116, v126, v120
	v_cvt_pk_bf16_f32 v117, v121, v117
	v_add_f32_e32 v106, 1.0, v106
	global_store_dwordx4 v[122:123], v[114:117], off offset:256
	s_nop 0
	v_exp_f32_e32 v107, v107
	v_rcp_f32_e32 v116, v106
	v_add_f32_e32 v106, 1.0, v111
	v_mul_f32_e32 v111, 0xbfb8aa3b, v112
	v_exp_f32_e32 v111, v111
	v_exp_f32_e32 v110, v110
	v_add_f32_e32 v107, 1.0, v107
	v_pk_mul_f32 v[108:109], v[108:109], v[198:199] op_sel_hi:[1,0]
	v_exp_f32_e32 v108, v108
	v_rcp_f32_e32 v112, v107
	v_add_f32_e32 v107, 1.0, v111
	v_mul_f32_e32 v111, 0xbfb8aa3b, v113
	v_exp_f32_e32 v111, v111
	v_exp_f32_e32 v109, v109
	v_add_f32_e32 v110, 1.0, v110
	v_rcp_f32_e32 v110, v110
	v_rcp_f32_e32 v106, v106
	v_add_f32_e32 v108, 1.0, v108
	v_rcp_f32_e32 v113, v108
	v_add_f32_e32 v108, 1.0, v111
	v_add_f32_e32 v109, 1.0, v109
	v_pk_mul_f32 v[98:99], v[98:99], v[198:199] op_sel_hi:[1,0]
	v_or_b32_e32 v114, 16, v160
	v_rcp_f32_e32 v107, v107
	v_rcp_f32_e32 v108, v108
	v_rcp_f32_e32 v109, v109
	v_exp_f32_e32 v98, v98
	v_pk_mul_f32 v[102:103], v[102:103], v[198:199] op_sel_hi:[1,0]
	v_ashrrev_i32_e32 v115, 31, v114
	v_exp_f32_e32 v103, v103
	v_cvt_pk_bf16_f32 v106, v110, v106
	v_lshlrev_b64 v[110:111], 11, v[114:115]
	v_lshl_add_u64 v[110:111], s[24:25], 0, v[110:111]
	v_cvt_pk_bf16_f32 v107, v107, v108
	v_cvt_pk_bf16_f32 v108, v116, v112
	v_cvt_pk_bf16_f32 v109, v113, v109
	v_lshl_add_u64 v[110:111], v[110:111], 0, v[124:125]
	v_add_f32_e32 v98, 1.0, v98
	global_store_dwordx4 v[110:111], v[106:109], off
	v_exp_f32_e32 v99, v99
	v_pk_mul_f32 v[100:101], v[100:101], v[198:199] op_sel_hi:[1,0]
	v_rcp_f32_e32 v106, v98
	v_add_f32_e32 v98, 1.0, v103
	v_mul_f32_e32 v103, 0xbfb8aa3b, v104
	v_exp_f32_e32 v103, v103
	v_add_f32_e32 v99, 1.0, v99
	v_exp_f32_e32 v100, v100
	v_rcp_f32_e32 v104, v99
	v_add_f32_e32 v99, 1.0, v103
	v_mul_f32_e32 v103, 0xbfb8aa3b, v105
	v_exp_f32_e32 v102, v102
	v_exp_f32_e32 v103, v103
	v_exp_f32_e32 v101, v101
	v_add_f32_e32 v100, 1.0, v100
	v_add_f32_e32 v102, 1.0, v102
	v_rcp_f32_e32 v105, v100
	v_add_f32_e32 v100, 1.0, v103
	v_add_f32_e32 v101, 1.0, v101
	v_pk_mul_f32 v[90:91], v[90:91], v[198:199] op_sel_hi:[1,0]
	v_rcp_f32_e32 v102, v102
	v_rcp_f32_e32 v98, v98
	v_rcp_f32_e32 v99, v99
	v_rcp_f32_e32 v100, v100
	v_rcp_f32_e32 v101, v101
	v_exp_f32_e32 v90, v90
	v_pk_mul_f32 v[94:95], v[94:95], v[198:199] op_sel_hi:[1,0]
	v_exp_f32_e32 v95, v95
	v_cvt_pk_bf16_f32 v98, v102, v98
	v_cvt_pk_bf16_f32 v99, v99, v100
	v_cvt_pk_bf16_f32 v100, v106, v104
	v_cvt_pk_bf16_f32 v101, v105, v101
	v_add_f32_e32 v90, 1.0, v90
	global_store_dwordx4 v[110:111], v[98:101], off offset:256
	s_nop 0
	v_exp_f32_e32 v91, v91
	v_rcp_f32_e32 v100, v90
	v_add_f32_e32 v90, 1.0, v95
	v_mul_f32_e32 v95, 0xbfb8aa3b, v96
	v_exp_f32_e32 v95, v95
	v_exp_f32_e32 v94, v94
	v_add_f32_e32 v91, 1.0, v91
	v_pk_mul_f32 v[92:93], v[92:93], v[198:199] op_sel_hi:[1,0]
	v_exp_f32_e32 v92, v92
	v_rcp_f32_e32 v96, v91
	v_add_f32_e32 v91, 1.0, v95
	v_mul_f32_e32 v95, 0xbfb8aa3b, v97
; __device__ __forceinline__ unsigned pkbf(float lo, float hi) { f32x2p v = {lo, hi}; bf16x2p b = __builtin_convertvector(v, bf16x2p); return __builtin_bit_cast(unsigned, b); }
; __device__ __forceinline__ float sigmoidf_(float x) { return __builtin_amdgcn_rcpf(1.0f + __builtin_amdgcn_exp2f(-x * LOG2E)); }
;     __device__ __forceinline__ void operator()(const f32x4 (&acc)[2][2][4][2], const Unit& u, int wr, int wc, int fr, int fq) const {
;     ...
;                         if constexpr (MODE == EPI_SIG) {
; #pragma unroll
;                             for (int e = 0; e < 4; ++e) { v0[e] = sigmoidf_(v0[e]); v1[e] = sigmoidf_(v1[e]); }
;                         }
;                         if constexpr (MODE == EPI_RELU2) {
; #pragma unroll
;                             for (int e = 0; e < 4; ++e) { float a = fmaxf(v0[e], 0.f), b = fmaxf(v1[e], 0.f); v0[e] = a * a; v1[e] = b * b; }
;                         }
;                         if constexpr (MODE == EPI_GATEMUL) {
;                             const u32x4 gw = *(const u32x4*)(G + off); v0 = v0 * bscale; v1 = v1 * bscale;
;                             v0[0] *= bflo(gw.x); v0[1] *= bfhi(gw.x); v0[2] *= bflo(gw.y); v0[3] *= bfhi(gw.y);
;                             v1[0] *= bflo(gw.z); v1[1] *= bfhi(gw.z); v1[2] *= bflo(gw.w); v1[3] *= bfhi(gw.w);
;                             if (!first) {
;                                 const u32x4 ow = *(const u32x4*)(O + off);
;                                 v0[0] += bflo(ow.x); v0[1] += bfhi(ow.x); v0[2] += bflo(ow.y); v0[3] += bfhi(ow.y);
;                                 v1[0] += bflo(ow.z); v1[1] += bfhi(ow.z); v1[2] += bflo(ow.w); v1[3] += bfhi(ow.w);
;                             }
;                         }
;                         u32x4 w; w.x = pkbf(v0[0], v0[1]); w.y = pkbf(v0[2], v0[3]); w.z = pkbf(v1[0], v1[1]); w.w = pkbf(v1[2], v1[3]);
;                         *(u32x4*)(O + off) = w;
	v_exp_f32_e32 v95, v95
	v_exp_f32_e32 v93, v93
	v_add_f32_e32 v94, 1.0, v94
	v_rcp_f32_e32 v94, v94
	v_rcp_f32_e32 v90, v90
	v_add_f32_e32 v92, 1.0, v92
	v_rcp_f32_e32 v97, v92
	v_add_f32_e32 v92, 1.0, v95
	v_add_f32_e32 v93, 1.0, v93
	v_pk_mul_f32 v[82:83], v[82:83], v[198:199] op_sel_hi:[1,0]
	v_or_b32_e32 v98, 32, v160
	v_rcp_f32_e32 v91, v91
	v_rcp_f32_e32 v92, v92
	v_rcp_f32_e32 v93, v93
	v_exp_f32_e32 v82, v82
	v_pk_mul_f32 v[86:87], v[86:87], v[198:199] op_sel_hi:[1,0]
	v_ashrrev_i32_e32 v99, 31, v98
	v_exp_f32_e32 v87, v87
	v_cvt_pk_bf16_f32 v90, v94, v90
	v_lshlrev_b64 v[94:95], 11, v[98:99]
	v_lshl_add_u64 v[94:95], s[24:25], 0, v[94:95]
	v_cvt_pk_bf16_f32 v91, v91, v92
	v_cvt_pk_bf16_f32 v92, v100, v96
	v_cvt_pk_bf16_f32 v93, v97, v93
	v_lshl_add_u64 v[94:95], v[94:95], 0, v[124:125]
	v_add_f32_e32 v82, 1.0, v82
	global_store_dwordx4 v[94:95], v[90:93], off
	v_exp_f32_e32 v83, v83
	v_pk_mul_f32 v[84:85], v[84:85], v[198:199] op_sel_hi:[1,0]
	v_rcp_f32_e32 v90, v82
	v_add_f32_e32 v82, 1.0, v87
	v_mul_f32_e32 v87, 0xbfb8aa3b, v88
	v_exp_f32_e32 v87, v87
	v_add_f32_e32 v83, 1.0, v83
	v_exp_f32_e32 v84, v84
	v_rcp_f32_e32 v88, v83
	v_add_f32_e32 v83, 1.0, v87
	v_mul_f32_e32 v87, 0xbfb8aa3b, v89
	v_exp_f32_e32 v86, v86
	v_exp_f32_e32 v87, v87
	v_exp_f32_e32 v85, v85
	v_add_f32_e32 v84, 1.0, v84
	v_add_f32_e32 v86, 1.0, v86
	v_rcp_f32_e32 v89, v84
	v_add_f32_e32 v84, 1.0, v87
	v_add_f32_e32 v85, 1.0, v85
	v_pk_mul_f32 v[74:75], v[74:75], v[198:199] op_sel_hi:[1,0]
	v_rcp_f32_e32 v86, v86
	v_rcp_f32_e32 v82, v82
	v_rcp_f32_e32 v83, v83
	v_rcp_f32_e32 v84, v84
	v_rcp_f32_e32 v85, v85
	v_exp_f32_e32 v74, v74
	v_pk_mul_f32 v[78:79], v[78:79], v[198:199] op_sel_hi:[1,0]
	v_exp_f32_e32 v79, v79
	v_cvt_pk_bf16_f32 v82, v86, v82
	v_cvt_pk_bf16_f32 v83, v83, v84
	v_cvt_pk_bf16_f32 v84, v90, v88
	v_cvt_pk_bf16_f32 v85, v89, v85
	v_add_f32_e32 v74, 1.0, v74
	global_store_dwordx4 v[94:95], v[82:85], off offset:256
	s_nop 0
	v_exp_f32_e32 v75, v75
	v_rcp_f32_e32 v84, v74
	v_add_f32_e32 v74, 1.0, v79
	v_mul_f32_e32 v79, 0xbfb8aa3b, v80
	v_exp_f32_e32 v79, v79
	v_exp_f32_e32 v78, v78
	v_add_f32_e32 v75, 1.0, v75
	v_pk_mul_f32 v[76:77], v[76:77], v[198:199] op_sel_hi:[1,0]
	v_exp_f32_e32 v76, v76
	v_rcp_f32_e32 v80, v75
	v_add_f32_e32 v75, 1.0, v79
	v_mul_f32_e32 v79, 0xbfb8aa3b, v81
	v_exp_f32_e32 v79, v79
	v_exp_f32_e32 v77, v77
	v_add_f32_e32 v78, 1.0, v78
	v_rcp_f32_e32 v78, v78
	v_rcp_f32_e32 v74, v74
	v_add_f32_e32 v76, 1.0, v76
	v_rcp_f32_e32 v81, v76
	v_add_f32_e32 v76, 1.0, v79
	v_add_f32_e32 v77, 1.0, v77
	v_pk_mul_f32 v[66:67], v[66:67], v[198:199] op_sel_hi:[1,0]
	v_or_b32_e32 v82, 48, v160
	v_rcp_f32_e32 v75, v75
	v_rcp_f32_e32 v76, v76
	v_rcp_f32_e32 v77, v77
	v_exp_f32_e32 v66, v66
	v_pk_mul_f32 v[70:71], v[70:71], v[198:199] op_sel_hi:[1,0]
	v_ashrrev_i32_e32 v83, 31, v82
	v_exp_f32_e32 v71, v71
	v_cvt_pk_bf16_f32 v74, v78, v74
	v_lshlrev_b64 v[78:79], 11, v[82:83]
	v_lshl_add_u64 v[78:79], s[24:25], 0, v[78:79]
	v_cvt_pk_bf16_f32 v75, v75, v76
	v_cvt_pk_bf16_f32 v76, v84, v80
	v_cvt_pk_bf16_f32 v77, v81, v77
	v_lshl_add_u64 v[78:79], v[78:79], 0, v[124:125]
	v_add_f32_e32 v66, 1.0, v66
	global_store_dwordx4 v[78:79], v[74:77], off
	v_exp_f32_e32 v67, v67
	v_pk_mul_f32 v[68:69], v[68:69], v[198:199] op_sel_hi:[1,0]
	v_rcp_f32_e32 v74, v66
	v_add_f32_e32 v66, 1.0, v71
	v_mul_f32_e32 v71, 0xbfb8aa3b, v72
	v_exp_f32_e32 v71, v71
	v_add_f32_e32 v67, 1.0, v67
	v_exp_f32_e32 v68, v68
	v_rcp_f32_e32 v72, v67
	v_add_f32_e32 v67, 1.0, v71
	v_mul_f32_e32 v71, 0xbfb8aa3b, v73
	v_exp_f32_e32 v70, v70
	v_exp_f32_e32 v71, v71
	v_exp_f32_e32 v69, v69
	v_add_f32_e32 v68, 1.0, v68
	v_add_f32_e32 v70, 1.0, v70
	v_rcp_f32_e32 v73, v68
	v_add_f32_e32 v68, 1.0, v71
	v_add_f32_e32 v69, 1.0, v69
	v_pk_mul_f32 v[58:59], v[58:59], v[198:199] op_sel_hi:[1,0]
	v_rcp_f32_e32 v70, v70
	v_rcp_f32_e32 v66, v66
	v_rcp_f32_e32 v67, v67
	v_rcp_f32_e32 v68, v68
	v_rcp_f32_e32 v69, v69
	v_exp_f32_e32 v58, v58
	v_pk_mul_f32 v[62:63], v[62:63], v[198:199] op_sel_hi:[1,0]
	v_exp_f32_e32 v63, v63
	v_cvt_pk_bf16_f32 v66, v70, v66
	v_cvt_pk_bf16_f32 v67, v67, v68
	v_cvt_pk_bf16_f32 v68, v74, v72
	v_cvt_pk_bf16_f32 v69, v73, v69
	v_add_f32_e32 v58, 1.0, v58
	global_store_dwordx4 v[78:79], v[66:69], off offset:256
	v_exp_f32_e32 v59, v59
	v_pk_mul_f32 v[60:61], v[60:61], v[198:199] op_sel_hi:[1,0]
	v_rcp_f32_e32 v66, v58
	v_add_f32_e32 v58, 1.0, v63
	v_mul_f32_e32 v63, 0xbfb8aa3b, v64
	v_exp_f32_e32 v63, v63
	v_add_f32_e32 v59, 1.0, v59
	v_exp_f32_e32 v60, v60
	v_rcp_f32_e32 v64, v59
	v_add_f32_e32 v59, 1.0, v63
	v_mul_f32_e32 v63, 0xbfb8aa3b, v65
	v_exp_f32_e32 v63, v63
	v_exp_f32_e32 v62, v62
	v_exp_f32_e32 v61, v61
	v_add_f32_e32 v60, 1.0, v60
	v_rcp_f32_e32 v65, v60
	v_add_f32_e32 v60, 1.0, v63
	v_add_f32_e32 v62, 1.0, v62
	v_rcp_f32_e32 v59, v59
	v_rcp_f32_e32 v60, v60
	v_add_f32_e32 v61, 1.0, v61
	v_pk_mul_f32 v[50:51], v[50:51], v[198:199] op_sel_hi:[1,0]
	v_rcp_f32_e32 v62, v62
	v_rcp_f32_e32 v58, v58
	v_rcp_f32_e32 v61, v61
	v_exp_f32_e32 v50, v50
	v_pk_mul_f32 v[54:55], v[54:55], v[198:199] op_sel_hi:[1,0]
	v_exp_f32_e32 v55, v55
	s_mov_b32 s4, 0x40000
	v_cvt_pk_bf16_f32 v59, v59, v60
	v_cvt_pk_bf16_f32 v60, v66, v64
	v_add_co_u32_e32 v64, vcc, s4, v122
	v_cvt_pk_bf16_f32 v58, v62, v58
	v_cvt_pk_bf16_f32 v61, v65, v61
	v_addc_co_u32_e32 v65, vcc, 0, v123, vcc
	v_add_f32_e32 v50, 1.0, v50
	global_store_dwordx4 v[64:65], v[58:61], off
	v_exp_f32_e32 v51, v51
	v_pk_mul_f32 v[52:53], v[52:53], v[198:199] op_sel_hi:[1,0]
	v_rcp_f32_e32 v58, v50
	v_add_f32_e32 v50, 1.0, v55
	v_mul_f32_e32 v55, 0xbfb8aa3b, v56
	v_exp_f32_e32 v55, v55
	v_add_f32_e32 v51, 1.0, v51
; __device__ __forceinline__ unsigned pkbf(float lo, float hi) { f32x2p v = {lo, hi}; bf16x2p b = __builtin_convertvector(v, bf16x2p); return __builtin_bit_cast(unsigned, b); }
; __device__ __forceinline__ float sigmoidf_(float x) { return __builtin_amdgcn_rcpf(1.0f + __builtin_amdgcn_exp2f(-x * LOG2E)); }
;     __device__ __forceinline__ void operator()(const f32x4 (&acc)[2][2][4][2], const Unit& u, int wr, int wc, int fr, int fq) const {
;     ...
;                         if constexpr (MODE == EPI_SIG) {
; #pragma unroll
;                             for (int e = 0; e < 4; ++e) { v0[e] = sigmoidf_(v0[e]); v1[e] = sigmoidf_(v1[e]); }
;                         }
;                         if constexpr (MODE == EPI_RELU2) {
; #pragma unroll
;                             for (int e = 0; e < 4; ++e) { float a = fmaxf(v0[e], 0.f), b = fmaxf(v1[e], 0.f); v0[e] = a * a; v1[e] = b * b; }
;                         }
;                         if constexpr (MODE == EPI_GATEMUL) {
;                             const u32x4 gw = *(const u32x4*)(G + off); v0 = v0 * bscale; v1 = v1 * bscale;
;                             v0[0] *= bflo(gw.x); v0[1] *= bfhi(gw.x); v0[2] *= bflo(gw.y); v0[3] *= bfhi(gw.y);
;                             v1[0] *= bflo(gw.z); v1[1] *= bfhi(gw.z); v1[2] *= bflo(gw.w); v1[3] *= bfhi(gw.w);
;                             if (!first) {
;                                 const u32x4 ow = *(const u32x4*)(O + off);
;                                 v0[0] += bflo(ow.x); v0[1] += bfhi(ow.x); v0[2] += bflo(ow.y); v0[3] += bfhi(ow.y);
;                                 v1[0] += bflo(ow.z); v1[1] += bfhi(ow.z); v1[2] += bflo(ow.w); v1[3] += bfhi(ow.w);
;                             }
;                         }
;                         u32x4 w; w.x = pkbf(v0[0], v0[1]); w.y = pkbf(v0[2], v0[3]); w.z = pkbf(v1[0], v1[1]); w.w = pkbf(v1[2], v1[3]);
;                         *(u32x4*)(O + off) = w;
	v_exp_f32_e32 v52, v52
	v_rcp_f32_e32 v56, v51
	v_add_f32_e32 v51, 1.0, v55
	v_mul_f32_e32 v55, 0xbfb8aa3b, v57
	v_exp_f32_e32 v54, v54
	v_exp_f32_e32 v55, v55
	v_exp_f32_e32 v53, v53
	v_add_f32_e32 v52, 1.0, v52
	v_add_f32_e32 v54, 1.0, v54
	v_rcp_f32_e32 v57, v52
	v_add_f32_e32 v52, 1.0, v55
	v_add_f32_e32 v53, 1.0, v53
	v_pk_mul_f32 v[42:43], v[42:43], v[198:199] op_sel_hi:[1,0]
	v_rcp_f32_e32 v54, v54
	v_rcp_f32_e32 v50, v50
	v_rcp_f32_e32 v51, v51
	v_rcp_f32_e32 v52, v52
	v_rcp_f32_e32 v53, v53
	v_exp_f32_e32 v42, v42
	v_pk_mul_f32 v[46:47], v[46:47], v[198:199] op_sel_hi:[1,0]
	v_exp_f32_e32 v47, v47
	s_mov_b64 s[10:11], 0x40000
	v_lshl_add_u64 v[62:63], v[122:123], 0, s[10:11]
	v_cvt_pk_bf16_f32 v50, v54, v50
	v_cvt_pk_bf16_f32 v51, v51, v52
	v_cvt_pk_bf16_f32 v52, v58, v56
	v_cvt_pk_bf16_f32 v53, v57, v53
	v_add_f32_e32 v42, 1.0, v42
	global_store_dwordx4 v[62:63], v[50:53], off offset:256
	v_exp_f32_e32 v43, v43
	v_pk_mul_f32 v[44:45], v[44:45], v[198:199] op_sel_hi:[1,0]
	v_rcp_f32_e32 v50, v42
	v_add_f32_e32 v42, 1.0, v47
	v_mul_f32_e32 v47, 0xbfb8aa3b, v48
	v_exp_f32_e32 v47, v47
	v_add_f32_e32 v43, 1.0, v43
	v_exp_f32_e32 v44, v44
	v_rcp_f32_e32 v48, v43
	v_add_f32_e32 v43, 1.0, v47
	v_mul_f32_e32 v47, 0xbfb8aa3b, v49
	v_exp_f32_e32 v47, v47
	v_exp_f32_e32 v46, v46
	v_exp_f32_e32 v45, v45
	v_add_f32_e32 v44, 1.0, v44
	v_rcp_f32_e32 v49, v44
	v_add_f32_e32 v44, 1.0, v47
	v_add_f32_e32 v46, 1.0, v46
	v_rcp_f32_e32 v43, v43
	v_rcp_f32_e32 v44, v44
	v_add_f32_e32 v45, 1.0, v45
	v_pk_mul_f32 v[34:35], v[34:35], v[198:199] op_sel_hi:[1,0]
	v_rcp_f32_e32 v46, v46
	v_rcp_f32_e32 v42, v42
	v_rcp_f32_e32 v45, v45
	v_exp_f32_e32 v34, v34
	v_pk_mul_f32 v[38:39], v[38:39], v[198:199] op_sel_hi:[1,0]
	v_exp_f32_e32 v39, v39
	s_mov_b32 s4, 0x48000
	v_cvt_pk_bf16_f32 v43, v43, v44
	v_cvt_pk_bf16_f32 v44, v50, v48
	v_add_co_u32_e32 v48, vcc, s4, v122
	v_cvt_pk_bf16_f32 v42, v46, v42
	v_cvt_pk_bf16_f32 v45, v49, v45
	v_addc_co_u32_e32 v49, vcc, 0, v123, vcc
	v_add_f32_e32 v34, 1.0, v34
	global_store_dwordx4 v[48:49], v[42:45], off
	v_exp_f32_e32 v35, v35
	v_pk_mul_f32 v[36:37], v[36:37], v[198:199] op_sel_hi:[1,0]
	v_rcp_f32_e32 v42, v34
	v_add_f32_e32 v34, 1.0, v39
	v_mul_f32_e32 v39, 0xbfb8aa3b, v40
	v_exp_f32_e32 v39, v39
	v_add_f32_e32 v35, 1.0, v35
	v_exp_f32_e32 v36, v36
	v_rcp_f32_e32 v40, v35
	v_add_f32_e32 v35, 1.0, v39
	v_mul_f32_e32 v39, 0xbfb8aa3b, v41
	v_exp_f32_e32 v38, v38
	v_exp_f32_e32 v39, v39
	v_exp_f32_e32 v37, v37
	v_add_f32_e32 v36, 1.0, v36
	v_add_f32_e32 v38, 1.0, v38
	v_rcp_f32_e32 v41, v36
	v_add_f32_e32 v36, 1.0, v39
	v_add_f32_e32 v37, 1.0, v37
	v_pk_mul_f32 v[26:27], v[26:27], v[198:199] op_sel_hi:[1,0]
	v_rcp_f32_e32 v38, v38
	v_rcp_f32_e32 v34, v34
	v_rcp_f32_e32 v35, v35
	v_rcp_f32_e32 v36, v36
	v_rcp_f32_e32 v37, v37
	v_exp_f32_e32 v26, v26
	v_pk_mul_f32 v[30:31], v[30:31], v[198:199] op_sel_hi:[1,0]
	v_exp_f32_e32 v31, v31
	s_mov_b64 s[10:11], 0x48000
	v_lshl_add_u64 v[46:47], v[122:123], 0, s[10:11]
	v_cvt_pk_bf16_f32 v34, v38, v34
	v_cvt_pk_bf16_f32 v35, v35, v36
	v_cvt_pk_bf16_f32 v36, v42, v40
	v_cvt_pk_bf16_f32 v37, v41, v37
	v_add_f32_e32 v26, 1.0, v26
	global_store_dwordx4 v[46:47], v[34:37], off offset:256
	v_exp_f32_e32 v27, v27
	v_pk_mul_f32 v[28:29], v[28:29], v[198:199] op_sel_hi:[1,0]
	v_rcp_f32_e32 v34, v26
	v_add_f32_e32 v26, 1.0, v31
	v_mul_f32_e32 v31, 0xbfb8aa3b, v32
	v_exp_f32_e32 v31, v31
	v_add_f32_e32 v27, 1.0, v27
	v_exp_f32_e32 v28, v28
	v_rcp_f32_e32 v32, v27
	v_add_f32_e32 v27, 1.0, v31
	v_mul_f32_e32 v31, 0xbfb8aa3b, v33
	v_exp_f32_e32 v31, v31
	v_exp_f32_e32 v30, v30
	v_exp_f32_e32 v29, v29
	v_add_f32_e32 v28, 1.0, v28
	v_rcp_f32_e32 v33, v28
	v_add_f32_e32 v28, 1.0, v31
	v_add_f32_e32 v30, 1.0, v30
	v_rcp_f32_e32 v27, v27
	v_rcp_f32_e32 v28, v28
	v_add_f32_e32 v29, 1.0, v29
	v_pk_mul_f32 v[18:19], v[18:19], v[198:199] op_sel_hi:[1,0]
; __device__ __forceinline__ unsigned pkbf(float lo, float hi) { f32x2p v = {lo, hi}; bf16x2p b = __builtin_convertvector(v, bf16x2p); return __builtin_bit_cast(unsigned, b); }
; __device__ __forceinline__ float sigmoidf_(float x) { return __builtin_amdgcn_rcpf(1.0f + __builtin_amdgcn_exp2f(-x * LOG2E)); }
;     __device__ __forceinline__ void operator()(const f32x4 (&acc)[2][2][4][2], const Unit& u, int wr, int wc, int fr, int fq) const {
;     ...
;                         if constexpr (MODE == EPI_SIG) {
; #pragma unroll
;                             for (int e = 0; e < 4; ++e) { v0[e] = sigmoidf_(v0[e]); v1[e] = sigmoidf_(v1[e]); }
;                         }
;                         if constexpr (MODE == EPI_RELU2) {
; #pragma unroll
;                             for (int e = 0; e < 4; ++e) { float a = fmaxf(v0[e], 0.f), b = fmaxf(v1[e], 0.f); v0[e] = a * a; v1[e] = b * b; }
;                         }
;                         if constexpr (MODE == EPI_GATEMUL) {
;                             const u32x4 gw = *(const u32x4*)(G + off); v0 = v0 * bscale; v1 = v1 * bscale;
;                             v0[0] *= bflo(gw.x); v0[1] *= bfhi(gw.x); v0[2] *= bflo(gw.y); v0[3] *= bfhi(gw.y);
;                             v1[0] *= bflo(gw.z); v1[1] *= bfhi(gw.z); v1[2] *= bflo(gw.w); v1[3] *= bfhi(gw.w);
;                             if (!first) {
;                                 const u32x4 ow = *(const u32x4*)(O + off);
;                                 v0[0] += bflo(ow.x); v0[1] += bfhi(ow.x); v0[2] += bflo(ow.y); v0[3] += bfhi(ow.y);
;                                 v1[0] += bflo(ow.z); v1[1] += bfhi(ow.z); v1[2] += bflo(ow.w); v1[3] += bfhi(ow.w);
;                             }
;                         }
;                         u32x4 w; w.x = pkbf(v0[0], v0[1]); w.y = pkbf(v0[2], v0[3]); w.z = pkbf(v1[0], v1[1]); w.w = pkbf(v1[2], v1[3]);
;                         *(u32x4*)(O + off) = w;
	v_rcp_f32_e32 v30, v30
	v_rcp_f32_e32 v26, v26
	v_rcp_f32_e32 v29, v29
	v_exp_f32_e32 v18, v18
	v_pk_mul_f32 v[22:23], v[22:23], v[198:199] op_sel_hi:[1,0]
	v_exp_f32_e32 v23, v23
	s_mov_b32 s4, 0x50000
	v_cvt_pk_bf16_f32 v27, v27, v28
	v_cvt_pk_bf16_f32 v28, v34, v32
	v_add_co_u32_e32 v32, vcc, s4, v122
	v_cvt_pk_bf16_f32 v26, v30, v26
	v_cvt_pk_bf16_f32 v29, v33, v29
	v_addc_co_u32_e32 v33, vcc, 0, v123, vcc
	v_add_f32_e32 v18, 1.0, v18
	global_store_dwordx4 v[32:33], v[26:29], off
	v_exp_f32_e32 v19, v19
	v_pk_mul_f32 v[20:21], v[20:21], v[198:199] op_sel_hi:[1,0]
	v_rcp_f32_e32 v26, v18
	v_add_f32_e32 v18, 1.0, v23
	v_mul_f32_e32 v23, 0xbfb8aa3b, v24
	v_exp_f32_e32 v23, v23
	v_add_f32_e32 v19, 1.0, v19
	v_exp_f32_e32 v20, v20
	v_rcp_f32_e32 v24, v19
	v_add_f32_e32 v19, 1.0, v23
	v_mul_f32_e32 v23, 0xbfb8aa3b, v25
	v_exp_f32_e32 v22, v22
	v_exp_f32_e32 v23, v23
	v_exp_f32_e32 v21, v21
	v_add_f32_e32 v20, 1.0, v20
	v_add_f32_e32 v22, 1.0, v22
	v_rcp_f32_e32 v25, v20
	v_add_f32_e32 v20, 1.0, v23
	v_add_f32_e32 v21, 1.0, v21
	v_pk_mul_f32 v[10:11], v[10:11], v[198:199] op_sel_hi:[1,0]
	v_rcp_f32_e32 v22, v22
	v_rcp_f32_e32 v18, v18
	v_rcp_f32_e32 v19, v19
	v_rcp_f32_e32 v20, v20
	v_rcp_f32_e32 v21, v21
	v_exp_f32_e32 v10, v10
	v_pk_mul_f32 v[14:15], v[14:15], v[198:199] op_sel_hi:[1,0]
	v_exp_f32_e32 v15, v15
	s_mov_b64 s[10:11], 0x50000
	v_lshl_add_u64 v[30:31], v[122:123], 0, s[10:11]
	v_cvt_pk_bf16_f32 v18, v22, v18
	v_cvt_pk_bf16_f32 v19, v19, v20
	v_cvt_pk_bf16_f32 v20, v26, v24
	v_cvt_pk_bf16_f32 v21, v25, v21
	v_add_f32_e32 v10, 1.0, v10
	global_store_dwordx4 v[30:31], v[18:21], off offset:256
	v_exp_f32_e32 v11, v11
	v_pk_mul_f32 v[12:13], v[12:13], v[198:199] op_sel_hi:[1,0]
	v_rcp_f32_e32 v18, v10
	v_add_f32_e32 v10, 1.0, v15
	v_mul_f32_e32 v15, 0xbfb8aa3b, v16
	v_exp_f32_e32 v15, v15
	v_add_f32_e32 v11, 1.0, v11
	v_exp_f32_e32 v12, v12
	v_rcp_f32_e32 v16, v11
	v_add_f32_e32 v11, 1.0, v15
	v_mul_f32_e32 v15, 0xbfb8aa3b, v17
	v_exp_f32_e32 v15, v15
	v_exp_f32_e32 v14, v14
	v_exp_f32_e32 v13, v13
	v_add_f32_e32 v12, 1.0, v12
	v_rcp_f32_e32 v17, v12
	v_add_f32_e32 v12, 1.0, v15
	v_add_f32_e32 v14, 1.0, v14
	v_rcp_f32_e32 v11, v11
	v_rcp_f32_e32 v12, v12
	v_add_f32_e32 v13, 1.0, v13
	v_pk_mul_f32 v[2:3], v[2:3], v[198:199] op_sel_hi:[1,0]
	v_rcp_f32_e32 v14, v14
	v_rcp_f32_e32 v10, v10
	v_rcp_f32_e32 v13, v13
	v_exp_f32_e32 v2, v2
	v_pk_mul_f32 v[6:7], v[6:7], v[198:199] op_sel_hi:[1,0]
	v_exp_f32_e32 v7, v7
	s_mov_b32 s4, 0x58000
	v_cvt_pk_bf16_f32 v11, v11, v12
	v_cvt_pk_bf16_f32 v12, v18, v16
	v_add_co_u32_e32 v16, vcc, s4, v122
	v_cvt_pk_bf16_f32 v10, v14, v10
	v_cvt_pk_bf16_f32 v13, v17, v13
	v_addc_co_u32_e32 v17, vcc, 0, v123, vcc
	v_add_f32_e32 v2, 1.0, v2
	global_store_dwordx4 v[16:17], v[10:13], off
	v_exp_f32_e32 v3, v3
	v_pk_mul_f32 v[4:5], v[4:5], v[198:199] op_sel_hi:[1,0]
	v_rcp_f32_e32 v10, v2
	v_add_f32_e32 v2, 1.0, v7
	v_mul_f32_e32 v7, 0xbfb8aa3b, v8
	v_exp_f32_e32 v7, v7
	v_add_f32_e32 v3, 1.0, v3
	v_exp_f32_e32 v4, v4
	v_rcp_f32_e32 v8, v3
	v_add_f32_e32 v3, 1.0, v7
	v_mul_f32_e32 v7, 0xbfb8aa3b, v9
	v_exp_f32_e32 v6, v6
	v_exp_f32_e32 v7, v7
	v_exp_f32_e32 v5, v5
	v_add_f32_e32 v4, 1.0, v4
	v_add_f32_e32 v6, 1.0, v6
	v_rcp_f32_e32 v9, v4
	v_add_f32_e32 v4, 1.0, v7
	v_add_f32_e32 v5, 1.0, v5
	v_rcp_f32_e32 v6, v6
	v_rcp_f32_e32 v2, v2
	v_rcp_f32_e32 v3, v3
	v_rcp_f32_e32 v4, v4
	v_rcp_f32_e32 v5, v5
	s_mov_b64 s[10:11], 0x58000
	v_lshl_add_u64 v[14:15], v[122:123], 0, s[10:11]
	v_cvt_pk_bf16_f32 v2, v6, v2
	v_cvt_pk_bf16_f32 v3, v3, v4
	v_cvt_pk_bf16_f32 v4, v10, v8
	v_cvt_pk_bf16_f32 v5, v9, v5
	s_andn2_b64 vcc, exec, s[38:39]
	s_mov_b64 s[38:39], -1
	global_store_dwordx4 v[14:15], v[2:5], off offset:256
	s_cbranch_vccnz .LBB0_595
	s_andn2_b64 vcc, exec, s[20:21]
	s_cbranch_vccnz .LBB0_594
	s_barrier
	s_branch .LBB0_594
